# D4: relu of MFMA scores without the redundant canonicalising max; top-k radix select stops refining once the chosen bin is taken whole
# speedup vs baseline: 1.1635x; 1.0064x over previous
; __device__ __forceinline__ void dsa_index_phase(const Params& p, unsigned char* smem) {
;     ...
;                 f32x4 sc = {0.f, 0.f, 0.f, 0.f}, sd = {0.f, 0.f, 0.f, 0.f};
; #pragma unroll
;                 for (int h = 0; h < 8; ++h) {
;                     f32x4 acc = {0.f, 0.f, 0.f, 0.f}, acd = {0.f, 0.f, 0.f, 0.f};
;                     acc = __builtin_amdgcn_mfma_f32_16x16x32_f16(k0, qf[h][0], acc, 0, 0, 0);
;                     acd = __builtin_amdgcn_mfma_f32_16x16x32_f16(k2, qf[h][0], acd, 0, 0, 0);
;                     acc = __builtin_amdgcn_mfma_f32_16x16x32_f16(k1, qf[h][1], acc, 0, 0, 0);
;                     acd = __builtin_amdgcn_mfma_f32_16x16x32_f16(k3, qf[h][1], acd, 0, 0, 0);
; #pragma unroll
;                     for (int jj = 0; jj < 4; ++jj) { sc[jj] += fmaxf(acc[jj], 0.f) * wq[h]; sd[jj] += fmaxf(acd[jj], 0.f) * wq[h]; }
;                 }
;                 *(f32x4*)(SC + r * ROWP + s0 + q * 4) = sc;
;                 if (two) *(f32x4*)(SC + r * ROWP + s1 + q * 4) = sd;
.LBB0_119:
	s_or_b64 exec, exec, s[8:9]
	v_mfma_f32_16x16x32_f16 v[16:19], v[116:119], v[32:35], 0
	v_cmp_ge_i32_e64 s[0:1], s12, v20
	v_mfma_f32_16x16x32_f16 v[26:29], v[112:115], v[36:39], v[16:19]
	v_mfma_f32_16x16x32_f16 v[22:25], v[108:111], v[32:35], 0
	v_mfma_f32_16x16x32_f16 v[16:19], v[104:107], v[36:39], v[22:25]
	s_nop 5
	s_nop 0
	v_max_f32_e32 v208, 0, v26
	s_nop 0
	v_max_f32_e32 v209, 0, v27
	s_nop 0
	v_max_f32_e32 v210, 0, v28
	v_max_f32_e32 v20, v29, v29
	v_mfma_f32_16x16x32_f16 v[28:31], v[116:119], v[56:59], 0
	v_max_f32_e32 v211, 0, v20
	v_pk_fma_f32 v[210:211], v[132:133], v[210:211], 0 op_sel_hi:[1,1,0]
	v_mfma_f32_16x16x32_f16 v[22:25], v[116:119], v[40:43], 0
	v_mfma_f32_16x16x32_f16 v[120:123], v[108:111], v[40:43], 0
	v_mfma_f32_16x16x32_f16 v[28:31], v[112:115], v[60:63], v[28:31]
	v_mfma_f32_16x16x32_f16 v[24:27], v[112:115], v[44:47], v[22:25]
	v_mfma_f32_16x16x32_f16 v[20:23], v[104:107], v[44:47], v[120:123]
	s_nop 5
	s_nop 0
	v_max_f32_e32 v216, 0, v28
	s_nop 0
	v_mfma_f32_16x16x32_f16 v[120:123], v[116:119], v[64:67], 0
	v_max_f32_e32 v217, 0, v29
	s_nop 0
	v_max_f32_e32 v218, 0, v30
	v_max_f32_e32 v195, v31, v31
	v_mfma_f32_16x16x32_f16 v[28:31], v[112:115], v[68:71], v[120:123]
	v_max_f32_e32 v219, 0, v195
	s_nop 0
	v_max_f32_e32 v212, 0, v24
	v_mfma_f32_16x16x32_f16 v[120:123], v[116:119], v[72:75], 0
	s_nop 0
	s_nop 2
	s_nop 0
	v_max_f32_e32 v220, 0, v28
	s_nop 0
	v_max_f32_e32 v221, 0, v29
	s_nop 0
	v_max_f32_e32 v222, 0, v30
	s_nop 0
	v_max_f32_e32 v223, 0, v31
	v_mfma_f32_16x16x32_f16 v[28:31], v[112:115], v[76:79], v[120:123]
	v_max_f32_e32 v213, 0, v25
	s_nop 0
	v_max_f32_e32 v214, 0, v26
	v_mfma_f32_16x16x32_f16 v[120:123], v[116:119], v[80:83], 0
	s_nop 0
	s_nop 2
	s_nop 0
	v_max_f32_e32 v224, 0, v28
	v_mfma_f32_16x16x32_f16 v[120:123], v[112:115], v[84:87], v[120:123]
	s_nop 0
	v_max_f32_e32 v225, 0, v29
	s_nop 0
	v_mfma_f32_16x16x32_f16 v[204:207], v[116:119], v[88:91], 0
	v_max_f32_e32 v238, 0, v30
	s_nop 2
	s_nop 0
	v_max_f32_e32 v240, 0, v120
	s_nop 0
	v_max_f32_e32 v241, 0, v121
	s_nop 0
	v_max_f32_e32 v246, 0, v122
	v_max_f32_e32 v195, v123, v123
	v_mfma_f32_16x16x32_f16 v[120:123], v[112:115], v[92:95], v[204:207]
	s_nop 0
	v_max_f32_e32 v215, 0, v27
	v_max_f32_e32 v239, 0, v31
	v_mfma_f32_16x16x32_f16 v[116:119], v[116:119], v[96:99], 0
	v_max_f32_e32 v247, 0, v195
	s_nop 2
	s_nop 0
	v_max_f32_e32 v204, 0, v120
	s_nop 0
	v_max_f32_e32 v205, 0, v121
	s_nop 0
	v_max_f32_e32 v206, 0, v122
	s_nop 0
	v_max_f32_e32 v207, 0, v123
	v_mfma_f32_16x16x32_f16 v[118:121], v[112:115], v[100:103], v[116:119]
	v_fma_f32 v210, v134, v214, v210
	v_fma_f32 v211, v135, v215, v211
	v_pk_fma_f32 v[210:211], v[136:137], v[218:219], v[210:211]
	v_mfma_f32_16x16x32_f16 v[24:27], v[108:111], v[56:59], 0
	v_fma_f32 v210, v138, v222, v210
	v_fma_f32 v211, v139, v223, v211
	s_nop 1
	s_nop 0
	v_max_f32_e32 v123, 0, v119
	v_pk_fma_f32 v[116:117], v[132:133], v[208:209], 0 op_sel_hi:[1,1,0]
	s_nop 0
	v_pk_fma_f32 v[116:117], v[134:135], v[212:213], v[116:117]
	v_max_f32_e32 v122, 0, v118
	v_pk_fma_f32 v[116:117], v[136:137], v[216:217], v[116:117]
	s_nop 0
	v_pk_fma_f32 v[116:117], v[138:139], v[220:221], v[116:117]
	v_mfma_f32_16x16x32_f16 v[28:31], v[108:111], v[64:67], 0
	v_fma_f32 v208, v140, v224, v116
	v_fma_f32 v209, v141, v225, v117
	v_max_f32_e32 v195, v121, v121
	v_pk_fma_f32 v[208:209], v[142:143], v[240:241], v[208:209]
	v_mfma_f32_16x16x32_f16 v[112:115], v[108:111], v[72:75], 0
	v_fma_f32 v204, v144, v204, v208
	v_fma_f32 v205, v145, v205, v209
	v_max_f32_e32 v208, 0, v120
	v_pk_fma_f32 v[204:205], v[146:147], v[122:123], v[204:205]
	v_mfma_f32_16x16x32_f16 v[116:119], v[108:111], v[80:83], 0
	v_fma_f32 v210, v140, v238, v210
	v_fma_f32 v211, v141, v239, v211
	v_max_f32_e32 v209, 0, v195
	v_pk_fma_f32 v[210:211], v[142:143], v[246:247], v[210:211]
	v_mfma_f32_16x16x32_f16 v[120:123], v[108:111], v[88:91], 0
	v_fma_f32 v206, v144, v206, v210
	v_fma_f32 v207, v145, v207, v211
	v_pk_fma_f32 v[206:207], v[146:147], v[208:209], v[206:207]
	v_mfma_f32_16x16x32_f16 v[108:111], v[108:111], v[96:99], 0
	ds_write_b128 v193, v[204:207]
	v_mfma_f32_16x16x32_f16 v[24:27], v[104:107], v[60:63], v[24:27]
	v_mfma_f32_16x16x32_f16 v[28:31], v[104:107], v[68:71], v[28:31]
	v_mfma_f32_16x16x32_f16 v[112:115], v[104:107], v[76:79], v[112:115]
	v_mfma_f32_16x16x32_f16 v[116:119], v[104:107], v[84:87], v[116:119]
	v_mfma_f32_16x16x32_f16 v[120:123], v[104:107], v[92:95], v[120:123]
	v_mfma_f32_16x16x32_f16 v[104:107], v[104:107], v[100:103], v[108:111]
	s_and_saveexec_b64 s[8:9], s[0:1]
	s_cbranch_execz .LBB0_116
	s_nop 2
	s_nop 0
	v_max_f32_e32 v109, 0, v115
	s_nop 0
	v_max_f32_e32 v111, 0, v119
	s_nop 0
	s_nop 0
	s_nop 0
	v_max_f32_e32 v115, 0, v123
	v_max_f32_e32 v16, 0, v16
	s_nop 0
	s_nop 0
	v_max_f32_e32 v17, 0, v17
	s_nop 0
	s_nop 0
	v_max_f32_e32 v20, 0, v20
	v_max_f32_e32 v112, 0, v112
	s_nop 0
	v_max_f32_e32 v21, 0, v21
	v_pk_fma_f32 v[16:17], v[132:133], v[16:17], 0 op_sel_hi:[1,1,0]
	s_nop 0
	v_max_f32_e32 v19, 0, v19
	s_nop 0
	v_max_f32_e32 v116, 0, v116
	s_nop 0
	v_pk_fma_f32 v[16:17], v[134:135], v[20:21], v[16:17]
	v_max_f32_e32 v18, 0, v18
	s_nop 0
	v_max_f32_e32 v23, 0, v23
	s_nop 0
	s_nop 0
	v_max_f32_e32 v120, 0, v120
	s_nop 0
	s_nop 0
	v_max_f32_e32 v22, 0, v22
	s_nop 0
	v_pk_fma_f32 v[18:19], v[132:133], v[18:19], 0 op_sel_hi:[1,1,0]
	v_max_f32_e32 v27, 0, v27
	s_nop 0
	v_max_f32_e32 v24, 0, v24
	s_nop 0
	v_max_f32_e32 v25, 0, v25
	s_nop 0
	v_max_f32_e32 v113, 0, v113
	s_nop 0
	v_max_f32_e32 v26, 0, v26
	s_nop 0
	v_pk_fma_f32 v[18:19], v[134:135], v[22:23], v[18:19]
	v_max_f32_e32 v31, 0, v31
	v_max_f32_e32 v28, 0, v28
	v_max_f32_e32 v29, 0, v29
	v_max_f32_e32 v117, 0, v117
	s_nop 0
	v_pk_fma_f32 v[16:17], v[136:137], v[24:25], v[16:17]
	v_max_f32_e32 v30, 0, v30
	s_nop 0
	v_pk_fma_f32 v[18:19], v[136:137], v[26:27], v[18:19]
	v_max_f32_e32 v121, 0, v121
	v_pk_fma_f32 v[16:17], v[138:139], v[28:29], v[16:17]
	v_max_f32_e32 v108, 0, v114
	s_nop 0
	v_pk_fma_f32 v[18:19], v[138:139], v[30:31], v[18:19]
	v_pk_fma_f32 v[16:17], v[140:141], v[112:113], v[16:17]
	v_max_f32_e32 v110, 0, v118
	s_nop 0
	v_pk_fma_f32 v[18:19], v[140:141], v[108:109], v[18:19]
	s_nop 0
	s_nop 0
	s_nop 0
	v_pk_fma_f32 v[16:17], v[142:143], v[116:117], v[16:17]
	v_max_f32_e32 v114, 0, v122
	v_max_f32_e32 v20, v106, v106
	v_pk_fma_f32 v[18:19], v[142:143], v[110:111], v[18:19]
	v_max_f32_e32 v107, 0, v107
	v_max_f32_e32 v104, 0, v104
	v_max_f32_e32 v105, 0, v105
	v_pk_fma_f32 v[16:17], v[144:145], v[120:121], v[16:17]
	v_max_f32_e32 v106, 0, v20
	v_pk_fma_f32 v[18:19], v[144:145], v[114:115], v[18:19]
	v_pk_fma_f32 v[16:17], v[146:147], v[104:105], v[16:17]
	v_pk_fma_f32 v[18:19], v[146:147], v[106:107], v[18:19]
	ds_write_b128 v193, v[16:19] offset:512
	s_branch .LBB0_116

; __device__ __forceinline__ void dsa_index_phase(const Params& p, unsigned char* smem) {
;     ...
;                 for (int pass = 0; pass < 4; ++pass) {
;                     const int shift = 24 - 8 * pass;
;                     const unsigned hmask = pass == 0 ? 0u : (0xFFFFFFFFu << (shift + 8));
;                     *(u32x4*)(H + lane * 4) = (u32x4){0u, 0u, 0u, 0u};
;                     asm volatile("s_waitcnt lgkmcnt(0)" ::: "memory");
; #pragma unroll
;                     for (int i = 0; i < 32; ++i) if (i < ni) { const unsigned uu = u[i]; if (uu != 0u && (uu & hmask) == prefix) atomicAdd(H + ((uu >> shift) & 255u), 1u); }
;                     asm volatile("s_waitcnt lgkmcnt(0)" ::: "memory");
;                     const u32x4 hv = *(const u32x4*)(H + lane * 4);
;                     const int tot = (int)(hv.x + hv.y + hv.z + hv.w);
;                     int rs = tot;
;                     rs += __builtin_amdgcn_update_dpp(0, rs, 0xB1, 0xF, 0xF, true);
;                     rs += __builtin_amdgcn_update_dpp(0, rs, 0x4E, 0xF, 0xF, true);
;                     rs += __builtin_amdgcn_update_dpp(0, rs, 0x141, 0xF, 0xF, true);
;                     rs += __builtin_amdgcn_update_dpp(0, rs, 0x140, 0xF, 0xF, true);
;                     int rowsel = 3, above = 0;
;                     {
;                         const int r3 = __builtin_amdgcn_readlane(rs, 48), r2 = __builtin_amdgcn_readlane(rs, 32), r1 = __builtin_amdgcn_readlane(rs, 16);
;                         if (need > r3) { above = r3; rowsel = 2; if (need > above + r2) { above += r2; rowsel = 1; if (need > above + r1) { above += r1; rowsel = 0; } } }
;                     }
;                     int lsel = rowsel * 16;
;                     for (int k = 15; k >= 0; --k) {
;                         const int cl = __builtin_amdgcn_readlane(tot, rowsel * 16 + k);
;                         if (need <= above + cl) { lsel = rowsel * 16 + k; break; }
;                         above += cl;
;                     }
;                     const int b3 = __builtin_amdgcn_readlane((int)hv.w, lsel), b2 = __builtin_amdgcn_readlane((int)hv.z, lsel), b1 = __builtin_amdgcn_readlane((int)hv.y, lsel);
;                     int bsel = 3;
;                     if (need > above + b3) { above += b3; bsel = 2; if (need > above + b2) { above += b2; bsel = 1; if (need > above + b1) { above += b1; bsel = 0; } } }
.Ltk_m31:
.Ltk_scan:
	ds_read_b128 v[132:135], v190
	s_waitcnt lgkmcnt(0)
	v_add_u32_e32 v136, v132, v133
	v_add_u32_e32 v137, v134, v135
	v_add_u32_e32 v136, v136, v137
	v_mov_b32_e32 v137, v136
	s_nop 1
	v_add_u32_dpp v137, v137, v137 row_shr:1 row_mask:0xf bank_mask:0xf bound_ctrl:1
	s_nop 1
	v_add_u32_dpp v137, v137, v137 row_shr:2 row_mask:0xf bank_mask:0xf bound_ctrl:1
	s_nop 1
	v_add_u32_dpp v137, v137, v137 row_shr:4 row_mask:0xf bank_mask:0xf bound_ctrl:1
	s_nop 1
	v_add_u32_dpp v137, v137, v137 row_shr:8 row_mask:0xf bank_mask:0xf bound_ctrl:1
	s_nop 1
	v_add_u32_dpp v137, v137, v137 row_bcast:15 row_mask:0xa bank_mask:0xf
	s_nop 1
	v_add_u32_dpp v137, v137, v137 row_bcast:31 row_mask:0xc bank_mask:0xf
	s_nop 1
	v_cmp_le_u32_e64 s[2:3], s82, v137
	s_ff1_i32_b64 s16, s[2:3]
	v_readlane_b32 s17, v137, s16
	v_readlane_b32 s6, v136, s16
	v_readlane_b32 s0, v132, s16
	v_readlane_b32 s1, v133, s16
	v_readlane_b32 s2, v134, s16
	s_sub_u32 s17, s17, s6
	s_add_u32 s10, s17, s6
	s_add_u32 s0, s17, s0
	s_add_u32 s1, s0, s1
	s_add_u32 s2, s1, s2
	s_mov_b32 s3, 0
	s_cmp_gt_u32 s82, s0
	s_cselect_b32 s17, s0, s17
	s_addc_u32 s3, s3, 0
	s_cmp_gt_u32 s82, s1
	s_cselect_b32 s17, s1, s17
	s_addc_u32 s3, s3, 0
	s_cmp_gt_u32 s82, s2
	s_cselect_b32 s17, s2, s17
	s_addc_u32 s3, s3, 0
	s_cmp_le_u32 s82, s2
	s_cselect_b32 s10, s2, s10
	s_cmp_le_u32 s82, s1
	s_cselect_b32 s10, s1, s10
	s_cmp_le_u32 s82, s0
	s_cselect_b32 s10, s0, s10
	s_lshl_b32 s16, s16, 2
	s_add_u32 s16, s16, s3
	s_lshl_b32 s16, s16, s11
	s_or_b32 s33, s33, s16
	s_cmp_eq_u32 s82, s10
	s_cbranch_scc1 .Ltk_early
	s_sub_u32 s82, s82, s17
	s_cmp_eq_u32 s11, 0
	s_cbranch_scc1 .Ltk_compact
	s_sub_u32 s11, s11, 8
	s_branch .Ltk_pass
.Ltk_early:
	s_sub_u32 s82, s82, s17
	s_bfm_b32 s7, s11, 0
	s_or_b32 s33, s33, s7
